# bundle + sample-row skinny GEMM load batching (both K halves issued before the first wait)
# speedup vs baseline: 1.0086x; 1.0005x over previous
.LBB0_286:
	v_add_u32_e32 v0, s8, v37
	v_ashrrev_i32_e32 v1, 31, v0
	v_lshlrev_b64 v[0:1], 12, v[0:1]
	v_lshl_add_u64 v[2:3], v[12:13], 0, v[0:1]
	v_add_co_u32_e32 v0, vcc, 0x4000, v2
	s_nop 1
	v_addc_co_u32_e32 v1, vcc, 0, v3, vcc
	global_load_dwordx4 v[96:99], v[2:3], off
	global_load_dwordx4 v[100:103], v[8:9], off
	global_load_dwordx4 v[104:107], v[10:11], off
	global_load_dwordx4 v[108:111], v[0:1], off
	global_load_dwordx4 v[112:115], v[2:3], off offset:64
	global_load_dwordx4 v[116:119], v[20:21], off
	global_load_dwordx4 v[120:123], v[8:9], off offset:64
	global_load_dwordx4 v[124:127], v[0:1], off offset:64
	global_load_dwordx4 v[128:131], v[2:3], off offset:128
	global_load_dwordx4 v[132:135], v[8:9], off offset:128
	global_load_dwordx4 v[136:139], v[22:23], off
	global_load_dwordx4 v[140:143], v[0:1], off offset:128
	global_load_dwordx4 v[144:147], v[2:3], off offset:192
	global_load_dwordx4 v[148:151], v[8:9], off offset:192
	global_load_dwordx4 v[152:155], v[24:25], off
	global_load_dwordx4 v[156:159], v[0:1], off offset:192
	global_load_dwordx4 v[160:163], v[2:3], off offset:256
	global_load_dwordx4 v[164:167], v[8:9], off offset:256
	global_load_dwordx4 v[168:171], v[26:27], off
	global_load_dwordx4 v[172:175], v[0:1], off offset:256
	global_load_dwordx4 v[176:179], v[2:3], off offset:320
	global_load_dwordx4 v[180:183], v[8:9], off offset:320
	global_load_dwordx4 v[184:187], v[28:29], off
	global_load_dwordx4 v[196:199], v[0:1], off offset:320
	global_load_dwordx4 v[200:203], v[2:3], off offset:384
	global_load_dwordx4 v[204:207], v[8:9], off offset:384
	global_load_dwordx4 v[208:211], v[30:31], off
	global_load_dwordx4 v[212:215], v[0:1], off offset:384
	global_load_dwordx4 v[216:219], v[2:3], off offset:448
	global_load_dwordx4 v[220:223], v[0:1], off offset:448
	global_load_dwordx4 v[224:227], v[8:9], off offset:448
	global_load_dwordx4 v[228:231], v[32:33], off
	s_waitcnt vmcnt(30)
	v_mfma_f32_16x16x32_bf16 v[48:51], v[96:99], v[100:103], 0
	s_waitcnt vmcnt(29)
	v_mfma_f32_16x16x32_bf16 v[4:7], v[96:99], v[104:107], 0
	s_waitcnt vmcnt(28)
	v_mfma_f32_16x16x32_bf16 v[40:43], v[108:111], v[100:103], 0
	v_mfma_f32_16x16x32_bf16 v[44:47], v[108:111], v[104:107], 0
	s_waitcnt vmcnt(25)
	v_mfma_f32_16x16x32_bf16 v[48:51], v[112:115], v[120:123], v[48:51]
	v_mfma_f32_16x16x32_bf16 v[4:7], v[112:115], v[116:119], v[4:7]
	s_waitcnt vmcnt(24)
	v_mfma_f32_16x16x32_bf16 v[40:43], v[124:127], v[120:123], v[40:43]
	v_mfma_f32_16x16x32_bf16 v[44:47], v[124:127], v[116:119], v[44:47]
	s_waitcnt vmcnt(22)
	v_mfma_f32_16x16x32_bf16 v[48:51], v[128:131], v[132:135], v[48:51]
	s_waitcnt vmcnt(21)
	v_mfma_f32_16x16x32_bf16 v[4:7], v[128:131], v[136:139], v[4:7]
	s_waitcnt vmcnt(20)
	v_mfma_f32_16x16x32_bf16 v[40:43], v[140:143], v[132:135], v[40:43]
	v_mfma_f32_16x16x32_bf16 v[44:47], v[140:143], v[136:139], v[44:47]
	s_waitcnt vmcnt(18)
	v_mfma_f32_16x16x32_bf16 v[48:51], v[144:147], v[148:151], v[48:51]
	s_waitcnt vmcnt(17)
	v_mfma_f32_16x16x32_bf16 v[4:7], v[144:147], v[152:155], v[4:7]
	s_waitcnt vmcnt(16)
	v_mfma_f32_16x16x32_bf16 v[40:43], v[156:159], v[148:151], v[40:43]
	v_mfma_f32_16x16x32_bf16 v[44:47], v[156:159], v[152:155], v[44:47]
	s_waitcnt vmcnt(14)
	v_mfma_f32_16x16x32_bf16 v[48:51], v[160:163], v[164:167], v[48:51]
	s_waitcnt vmcnt(13)
	v_mfma_f32_16x16x32_bf16 v[4:7], v[160:163], v[168:171], v[4:7]
	s_waitcnt vmcnt(12)
	v_mfma_f32_16x16x32_bf16 v[40:43], v[172:175], v[164:167], v[40:43]
	v_mfma_f32_16x16x32_bf16 v[44:47], v[172:175], v[168:171], v[44:47]
	s_waitcnt vmcnt(10)
	v_mfma_f32_16x16x32_bf16 v[48:51], v[176:179], v[180:183], v[48:51]
	s_waitcnt vmcnt(9)
	v_mfma_f32_16x16x32_bf16 v[4:7], v[176:179], v[184:187], v[4:7]
	s_waitcnt vmcnt(8)
	v_mfma_f32_16x16x32_bf16 v[40:43], v[196:199], v[180:183], v[40:43]
	v_mfma_f32_16x16x32_bf16 v[44:47], v[196:199], v[184:187], v[44:47]
	s_waitcnt vmcnt(6)
	v_mfma_f32_16x16x32_bf16 v[48:51], v[200:203], v[204:207], v[48:51]
	s_waitcnt vmcnt(5)
	v_mfma_f32_16x16x32_bf16 v[4:7], v[200:203], v[208:211], v[4:7]
	s_waitcnt vmcnt(4)
	v_mfma_f32_16x16x32_bf16 v[40:43], v[212:215], v[204:207], v[40:43]
	v_mfma_f32_16x16x32_bf16 v[44:47], v[212:215], v[208:211], v[44:47]
	s_waitcnt vmcnt(1)
	v_mfma_f32_16x16x32_bf16 v[48:51], v[216:219], v[224:227], v[48:51]
	v_mfma_f32_16x16x32_bf16 v[40:43], v[220:223], v[224:227], v[40:43]
	s_waitcnt vmcnt(0)
	v_mfma_f32_16x16x32_bf16 v[0:3], v[220:223], v[228:231], v[44:47]
	v_mfma_f32_16x16x32_bf16 v[4:7], v[216:219], v[228:231], v[4:7]
	s_nop 7
	s_nop 1
	ds_write_b128 v38, v[48:51]
	s_nop 3
	ds_write_b128 v38, v[4:7] offset:2048
	ds_write_b128 v38, v[40:43] offset:1024
	ds_write_b128 v38, v[0:3] offset:3072
	s_waitcnt lgkmcnt(0)
	s_barrier
	s_and_saveexec_b64 s[6:7], s[4:5]
	s_cbranch_execz .LBB0_285
	ds_read_b128 v[0:3], v39
	ds_read_b128 v[4:7], v39 offset:1024
	ds_read_b128 v[40:43], v39 offset:4096
	s_waitcnt lgkmcnt(0)
	v_pk_add_f32 v[34:35], v[2:3], v[42:43]
	v_pk_add_f32 v[40:41], v[0:1], v[40:41]
	ds_read_b128 v[0:3], v39 offset:5120
	s_waitcnt lgkmcnt(0)
	v_pk_add_f32 v[6:7], v[6:7], v[2:3]
	v_pk_add_f32 v[4:5], v[4:5], v[0:1]
	ds_read_b128 v[0:3], v39 offset:8192
	s_waitcnt lgkmcnt(0)
	v_pk_add_f32 v[34:35], v[34:35], v[2:3]
	v_pk_add_f32 v[40:41], v[40:41], v[0:1]
	ds_read_b128 v[0:3], v39 offset:9216
	s_waitcnt lgkmcnt(0)
	v_pk_add_f32 v[6:7], v[6:7], v[2:3]
	v_pk_add_f32 v[4:5], v[4:5], v[0:1]
	ds_read_b128 v[0:3], v39 offset:12288
	s_waitcnt lgkmcnt(0)
	v_pk_add_f32 v[34:35], v[34:35], v[2:3]
	v_pk_add_f32 v[40:41], v[40:41], v[0:1]
	ds_read_b128 v[0:3], v39 offset:13312
	s_waitcnt lgkmcnt(0)
	v_pk_add_f32 v[6:7], v[6:7], v[2:3]
	v_pk_add_f32 v[4:5], v[4:5], v[0:1]
	ds_read_b128 v[0:3], v39 offset:16384
	s_waitcnt lgkmcnt(0)
	v_pk_add_f32 v[34:35], v[34:35], v[2:3]
	v_pk_add_f32 v[40:41], v[40:41], v[0:1]
	ds_read_b128 v[0:3], v39 offset:17408
	s_waitcnt lgkmcnt(0)
	v_pk_add_f32 v[6:7], v[6:7], v[2:3]
	v_pk_add_f32 v[4:5], v[4:5], v[0:1]
	ds_read_b128 v[0:3], v39 offset:20480
	s_waitcnt lgkmcnt(0)
	v_pk_add_f32 v[34:35], v[34:35], v[2:3]
	v_pk_add_f32 v[40:41], v[40:41], v[0:1]
	ds_read_b128 v[0:3], v39 offset:21504
	s_waitcnt lgkmcnt(0)
	v_pk_add_f32 v[6:7], v[6:7], v[2:3]
	v_pk_add_f32 v[4:5], v[4:5], v[0:1]
	ds_read_b128 v[0:3], v39 offset:24576
	s_waitcnt lgkmcnt(0)
	v_pk_add_f32 v[34:35], v[34:35], v[2:3]
	v_pk_add_f32 v[40:41], v[40:41], v[0:1]
	ds_read_b128 v[0:3], v39 offset:25600
	s_waitcnt lgkmcnt(0)
	v_pk_add_f32 v[42:43], v[6:7], v[2:3]
	v_pk_add_f32 v[44:45], v[4:5], v[0:1]
	ds_read_b128 v[0:3], v39 offset:28672
	s_waitcnt lgkmcnt(0)
	v_pk_add_f32 v[6:7], v[34:35], v[2:3]
	global_load_dword v34, v[14:15], off
	v_pk_add_f32 v[4:5], v[40:41], v[0:1]
	ds_read_b128 v[0:3], v39 offset:29696
	s_waitcnt lgkmcnt(0)
	v_pk_add_f32 v[2:3], v[42:43], v[2:3]
	v_pk_add_f32 v[0:1], v[44:45], v[0:1]
	s_waitcnt vmcnt(0)
	v_fmamk_f32 v34, v34, 0x3a000000, v233
	v_cmp_gt_f32_e32 vcc, s96, v34
	v_mul_f32_e32 v35, 0x4b800000, v34
	s_nop 0
	v_cndmask_b32_e32 v34, v34, v35, vcc
	v_rsq_f32_e32 v34, v34
	s_nop 0
	v_mul_f32_e32 v35, 0x45800000, v34
	v_cndmask_b32_e32 v40, v34, v35, vcc
	v_add_u32_e32 v34, s8, v36
	v_pk_mul_f32 v[4:5], v[4:5], v[40:41] op_sel_hi:[1,0]
	v_pk_mul_f32 v[6:7], v[6:7], v[40:41] op_sel_hi:[1,0]
	v_pk_mul_f32 v[0:1], v[0:1], v[40:41] op_sel_hi:[1,0]
	v_pk_mul_f32 v[2:3], v[2:3], v[40:41] op_sel_hi:[1,0]
	v_cmp_lt_i32_e32 vcc, s97, v34
	s_and_saveexec_b64 s[0:1], vcc
	s_xor_b64 s[2:3], exec, s[0:1]
	s_cbranch_execz .LBB0_291
	s_cmpk_lt_u32 s8, 0x1000
	s_mov_b64 s[0:1], 0
	s_cbranch_scc1 .LBB0_290
	v_mul_f32_e32 v35, 0xbfb8aa3b, v0
	v_exp_f32_e32 v40, v35
	v_mul_f32_e32 v35, 0xbfb8aa3b, v1
	v_exp_f32_e32 v41, v35
	v_mul_f32_e32 v35, 0xbfb8aa3b, v2
	v_exp_f32_e32 v42, v35
	v_mul_f32_e32 v35, 0xbfb8aa3b, v3
	v_exp_f32_e32 v43, v35
	v_pk_add_f32 v[40:41], v[40:41], 1.0 op_sel_hi:[1,0]
	v_pk_add_f32 v[42:43], v[42:43], 1.0 op_sel_hi:[1,0]
	s_nop 0
	v_div_scale_f32 v35, s[0:1], v43, v43, v3
	v_rcp_f32_e32 v44, v35
	s_nop 0
	v_fma_f32 v45, -v35, v44, 1.0
	v_fmac_f32_e32 v44, v45, v44
	v_div_scale_f32 v45, vcc, v3, v43, v3
	v_mul_f32_e32 v46, v45, v44
	v_fma_f32 v47, -v35, v46, v45
	v_fmac_f32_e32 v46, v47, v44
	v_fma_f32 v35, -v35, v46, v45
	v_div_fmas_f32 v35, v35, v44, v46
	v_div_fixup_f32 v3, v35, v43, v3
	v_div_scale_f32 v35, s[0:1], v42, v42, v2
	v_rcp_f32_e32 v43, v35
	s_nop 0
	v_fma_f32 v44, -v35, v43, 1.0
	v_fmac_f32_e32 v43, v44, v43
	v_div_scale_f32 v44, vcc, v2, v42, v2
	v_mul_f32_e32 v45, v44, v43
	v_fma_f32 v46, -v35, v45, v44
	v_fmac_f32_e32 v45, v46, v43
	v_fma_f32 v35, -v35, v45, v44
	v_div_fmas_f32 v35, v35, v43, v45
	v_div_fixup_f32 v2, v35, v42, v2
	v_div_scale_f32 v35, s[0:1], v41, v41, v1
	v_rcp_f32_e32 v42, v35
	s_nop 0
	v_fma_f32 v43, -v35, v42, 1.0
	v_fmac_f32_e32 v42, v43, v42
	v_div_scale_f32 v43, vcc, v1, v41, v1
	v_mul_f32_e32 v44, v43, v42
	v_fma_f32 v45, -v35, v44, v43
	v_fmac_f32_e32 v44, v45, v42
	v_fma_f32 v35, -v35, v44, v43
	v_div_fmas_f32 v35, v35, v42, v44
	v_div_fixup_f32 v1, v35, v41, v1
	v_div_scale_f32 v35, s[0:1], v40, v40, v0
	v_rcp_f32_e32 v41, v35
	s_mov_b64 s[0:1], 0x400
	v_fma_f32 v42, -v35, v41, 1.0
	v_fmac_f32_e32 v41, v42, v41
	v_div_scale_f32 v42, vcc, v0, v40, v0
	v_mul_f32_e32 v43, v42, v41
	v_fma_f32 v44, -v35, v43, v42
	v_fmac_f32_e32 v43, v44, v41
	v_fma_f32 v35, -v35, v43, v42
	v_div_fmas_f32 v35, v35, v41, v43
	v_div_fixup_f32 v0, v35, v40, v0

.LBB0_540:
	v_add_u32_e32 v24, s0, v29
	v_ashrrev_i32_e32 v25, 31, v24
	v_lshlrev_b64 v[24:25], 12, v[24:25]
	v_lshl_add_u64 v[26:27], v[4:5], 0, v[24:25]
	v_add_co_u32_e32 v24, vcc, 0x4000, v26
	s_nop 1
	v_addc_co_u32_e32 v25, vcc, 0, v27, vcc
	global_load_dwordx4 v[96:99], v[26:27], off
	global_load_dwordx4 v[100:103], v[0:1], off
	global_load_dwordx4 v[104:107], v[2:3], off
	global_load_dwordx4 v[108:111], v[24:25], off
	global_load_dwordx4 v[112:115], v[26:27], off offset:64
	global_load_dwordx4 v[116:119], v[10:11], off
	global_load_dwordx4 v[120:123], v[0:1], off offset:64
	global_load_dwordx4 v[124:127], v[24:25], off offset:64
	global_load_dwordx4 v[128:131], v[26:27], off offset:128
	global_load_dwordx4 v[132:135], v[0:1], off offset:128
	global_load_dwordx4 v[136:139], v[12:13], off
	global_load_dwordx4 v[140:143], v[24:25], off offset:128
	global_load_dwordx4 v[144:147], v[26:27], off offset:192
	global_load_dwordx4 v[148:151], v[0:1], off offset:192
	global_load_dwordx4 v[152:155], v[14:15], off
	global_load_dwordx4 v[156:159], v[24:25], off offset:192
	global_load_dwordx4 v[160:163], v[26:27], off offset:256
	global_load_dwordx4 v[164:167], v[0:1], off offset:256
	global_load_dwordx4 v[168:171], v[16:17], off
	global_load_dwordx4 v[172:175], v[24:25], off offset:256
	global_load_dwordx4 v[176:179], v[26:27], off offset:320
	global_load_dwordx4 v[180:183], v[0:1], off offset:320
	global_load_dwordx4 v[184:187], v[18:19], off
	global_load_dwordx4 v[196:199], v[24:25], off offset:320
	global_load_dwordx4 v[200:203], v[26:27], off offset:384
	global_load_dwordx4 v[204:207], v[0:1], off offset:384
	global_load_dwordx4 v[208:211], v[20:21], off
	global_load_dwordx4 v[212:215], v[24:25], off offset:384
	global_load_dwordx4 v[216:219], v[26:27], off offset:448
	global_load_dwordx4 v[220:223], v[24:25], off offset:448
	global_load_dwordx4 v[224:227], v[0:1], off offset:448
	global_load_dwordx4 v[228:231], v[22:23], off
	s_waitcnt vmcnt(30)
	v_mfma_f32_16x16x32_bf16 v[44:47], v[96:99], v[100:103], 0
	s_waitcnt vmcnt(29)
	v_mfma_f32_16x16x32_bf16 v[32:35], v[96:99], v[104:107], 0
	s_waitcnt vmcnt(28)
	v_mfma_f32_16x16x32_bf16 v[36:39], v[108:111], v[100:103], 0
	v_mfma_f32_16x16x32_bf16 v[40:43], v[108:111], v[104:107], 0
	s_waitcnt vmcnt(25)
	v_mfma_f32_16x16x32_bf16 v[44:47], v[112:115], v[120:123], v[44:47]
	v_mfma_f32_16x16x32_bf16 v[32:35], v[112:115], v[116:119], v[32:35]
	s_waitcnt vmcnt(24)
	v_mfma_f32_16x16x32_bf16 v[36:39], v[124:127], v[120:123], v[36:39]
	v_mfma_f32_16x16x32_bf16 v[40:43], v[124:127], v[116:119], v[40:43]
	s_waitcnt vmcnt(22)
	v_mfma_f32_16x16x32_bf16 v[44:47], v[128:131], v[132:135], v[44:47]
	s_waitcnt vmcnt(21)
	v_mfma_f32_16x16x32_bf16 v[32:35], v[128:131], v[136:139], v[32:35]
	s_waitcnt vmcnt(20)
	v_mfma_f32_16x16x32_bf16 v[36:39], v[140:143], v[132:135], v[36:39]
	v_mfma_f32_16x16x32_bf16 v[40:43], v[140:143], v[136:139], v[40:43]
	s_waitcnt vmcnt(18)
	v_mfma_f32_16x16x32_bf16 v[44:47], v[144:147], v[148:151], v[44:47]
	s_waitcnt vmcnt(17)
	v_mfma_f32_16x16x32_bf16 v[32:35], v[144:147], v[152:155], v[32:35]
	s_waitcnt vmcnt(16)
	v_mfma_f32_16x16x32_bf16 v[36:39], v[156:159], v[148:151], v[36:39]
	v_mfma_f32_16x16x32_bf16 v[40:43], v[156:159], v[152:155], v[40:43]
	s_waitcnt vmcnt(14)
	v_mfma_f32_16x16x32_bf16 v[44:47], v[160:163], v[164:167], v[44:47]
	s_waitcnt vmcnt(13)
	v_mfma_f32_16x16x32_bf16 v[32:35], v[160:163], v[168:171], v[32:35]
	s_waitcnt vmcnt(12)
	v_mfma_f32_16x16x32_bf16 v[36:39], v[172:175], v[164:167], v[36:39]
	v_mfma_f32_16x16x32_bf16 v[40:43], v[172:175], v[168:171], v[40:43]
	s_waitcnt vmcnt(10)
	v_mfma_f32_16x16x32_bf16 v[44:47], v[176:179], v[180:183], v[44:47]
	s_waitcnt vmcnt(9)
	v_mfma_f32_16x16x32_bf16 v[32:35], v[176:179], v[184:187], v[32:35]
	s_waitcnt vmcnt(8)
	v_mfma_f32_16x16x32_bf16 v[36:39], v[196:199], v[180:183], v[36:39]
	v_mfma_f32_16x16x32_bf16 v[40:43], v[196:199], v[184:187], v[40:43]
	s_waitcnt vmcnt(6)
	v_mfma_f32_16x16x32_bf16 v[44:47], v[200:203], v[204:207], v[44:47]
	s_waitcnt vmcnt(5)
	v_mfma_f32_16x16x32_bf16 v[32:35], v[200:203], v[208:211], v[32:35]
	s_waitcnt vmcnt(4)
	v_mfma_f32_16x16x32_bf16 v[36:39], v[212:215], v[204:207], v[36:39]
	v_mfma_f32_16x16x32_bf16 v[40:43], v[212:215], v[208:211], v[40:43]
	s_waitcnt vmcnt(1)
	v_mfma_f32_16x16x32_bf16 v[44:47], v[216:219], v[224:227], v[44:47]
	v_mfma_f32_16x16x32_bf16 v[36:39], v[220:223], v[224:227], v[36:39]
	s_waitcnt vmcnt(0)
	v_mfma_f32_16x16x32_bf16 v[24:27], v[220:223], v[228:231], v[40:43]
	v_mfma_f32_16x16x32_bf16 v[32:35], v[216:219], v[228:231], v[32:35]
	s_nop 7
	s_nop 1
	ds_write_b128 v30, v[44:47]
	s_nop 3
	ds_write_b128 v30, v[32:35] offset:2048
	ds_write_b128 v30, v[36:39] offset:1024
	ds_write_b128 v30, v[24:27] offset:3072
	s_waitcnt lgkmcnt(0)
	s_barrier
	s_and_saveexec_b64 s[10:11], s[6:7]
	s_cbranch_execz .LBB0_539
	ds_read_b128 v[24:27], v31
	ds_read_b128 v[32:35], v31 offset:1024
	ds_read_b128 v[36:39], v31 offset:4096
	s_waitcnt lgkmcnt(0)
	v_pk_add_f32 v[38:39], v[26:27], v[38:39]
	v_pk_add_f32 v[36:37], v[24:25], v[36:37]
	ds_read_b128 v[24:27], v31 offset:5120
	s_waitcnt lgkmcnt(0)
	v_pk_add_f32 v[34:35], v[34:35], v[26:27]
	v_pk_add_f32 v[32:33], v[32:33], v[24:25]
	ds_read_b128 v[24:27], v31 offset:8192
	s_waitcnt lgkmcnt(0)
	v_pk_add_f32 v[38:39], v[38:39], v[26:27]
	v_pk_add_f32 v[36:37], v[36:37], v[24:25]
	ds_read_b128 v[24:27], v31 offset:9216
	s_waitcnt lgkmcnt(0)
	v_pk_add_f32 v[34:35], v[34:35], v[26:27]
	v_pk_add_f32 v[32:33], v[32:33], v[24:25]
	ds_read_b128 v[24:27], v31 offset:12288
	s_waitcnt lgkmcnt(0)
	v_pk_add_f32 v[38:39], v[38:39], v[26:27]
	v_pk_add_f32 v[36:37], v[36:37], v[24:25]
	ds_read_b128 v[24:27], v31 offset:13312
	s_waitcnt lgkmcnt(0)
	v_pk_add_f32 v[34:35], v[34:35], v[26:27]
	v_pk_add_f32 v[32:33], v[32:33], v[24:25]
	ds_read_b128 v[24:27], v31 offset:16384
	s_waitcnt lgkmcnt(0)
	v_pk_add_f32 v[38:39], v[38:39], v[26:27]
	v_pk_add_f32 v[36:37], v[36:37], v[24:25]
	ds_read_b128 v[24:27], v31 offset:17408
	s_waitcnt lgkmcnt(0)
	v_pk_add_f32 v[34:35], v[34:35], v[26:27]
	v_pk_add_f32 v[32:33], v[32:33], v[24:25]
	ds_read_b128 v[24:27], v31 offset:20480
	s_waitcnt lgkmcnt(0)
	v_pk_add_f32 v[38:39], v[38:39], v[26:27]
	v_pk_add_f32 v[36:37], v[36:37], v[24:25]
	ds_read_b128 v[24:27], v31 offset:21504
	s_waitcnt lgkmcnt(0)
	v_pk_add_f32 v[34:35], v[34:35], v[26:27]
	v_pk_add_f32 v[32:33], v[32:33], v[24:25]
	ds_read_b128 v[24:27], v31 offset:24576
	s_waitcnt lgkmcnt(0)
	v_pk_add_f32 v[38:39], v[38:39], v[26:27]
	v_pk_add_f32 v[36:37], v[36:37], v[24:25]
	ds_read_b128 v[24:27], v31 offset:25600
	s_waitcnt lgkmcnt(0)
	v_pk_add_f32 v[34:35], v[34:35], v[26:27]
	v_pk_add_f32 v[32:33], v[32:33], v[24:25]
	ds_read_b128 v[24:27], v31 offset:28672
	s_waitcnt lgkmcnt(0)
	v_pk_add_f32 v[38:39], v[38:39], v[26:27]
	v_pk_add_f32 v[36:37], v[36:37], v[24:25]
	ds_read_b128 v[24:27], v31 offset:29696
	s_waitcnt lgkmcnt(0)
	v_pk_add_f32 v[32:33], v[32:33], v[24:25]
	v_add_u32_e32 v24, s0, v28
	v_ashrrev_i32_e32 v25, 31, v24
	v_lshl_add_u64 v[40:41], v[24:25], 1, v[6:7]
	v_pk_add_f32 v[34:35], v[34:35], v[26:27]
	global_load_dwordx4 v[24:27], v[40:41], off
	s_waitcnt vmcnt(0)
	v_lshlrev_b32_e32 v42, 16, v24
	v_and_b32_e32 v43, 0xffff0000, v24
	v_lshlrev_b32_e32 v24, 16, v25
	v_and_b32_e32 v25, 0xffff0000, v25
	v_lshlrev_b32_e32 v44, 16, v26
	v_and_b32_e32 v45, 0xffff0000, v26
	v_lshlrev_b32_e32 v26, 16, v27
	v_and_b32_e32 v27, 0xffff0000, v27
	v_pk_add_f32 v[38:39], v[38:39], v[24:25]
	v_pk_add_f32 v[36:37], v[36:37], v[42:43]
	v_pk_add_f32 v[34:35], v[34:35], v[26:27]
	v_cvt_pk_bf16_f32 v24, v36, v37
	v_cvt_pk_bf16_f32 v25, v38, v39
	v_pk_add_f32 v[32:33], v[32:33], v[44:45]
	s_nop 0
	v_cvt_pk_bf16_f32 v26, v32, v33
	v_cvt_pk_bf16_f32 v27, v34, v35
	global_store_dwordx4 v[40:41], v[24:27], off
	s_nop 1
	v_mul_f32_e32 v24, v37, v37
	v_mul_f32_e32 v25, v39, v39
	v_fmac_f32_e32 v24, v36, v36
	v_fmac_f32_e32 v25, v38, v38
	v_add_f32_e32 v24, v24, v25
	v_mul_f32_e32 v25, v33, v33
	v_mul_f32_e32 v26, v35, v35
	v_fmac_f32_e32 v25, v32, v32
	v_fmac_f32_e32 v26, v34, v34
	v_add_f32_e32 v25, v25, v26
	v_and_b32_e32 v26, 64, v238
	v_add_f32_e32 v24, v24, v25
	v_xor_b32_e32 v25, 16, v238
	v_add_u32_e32 v26, 64, v26
	v_cmp_lt_i32_e32 vcc, v25, v26
	s_nop 1
	v_cndmask_b32_e32 v25, v238, v25, vcc
	v_lshlrev_b32_e32 v25, 2, v25
	ds_bpermute_b32 v25, v25, v24
	s_waitcnt lgkmcnt(0)
	v_add_f32_e32 v24, v24, v25
	v_xor_b32_e32 v25, 32, v238
	v_cmp_lt_i32_e32 vcc, v25, v26
	s_nop 1
	v_cndmask_b32_e32 v25, v238, v25, vcc
	v_lshlrev_b32_e32 v25, 2, v25
	ds_bpermute_b32 v25, v25, v24
	s_and_b64 exec, exec, s[8:9]
	s_cbranch_execz .LBB0_539
	s_waitcnt lgkmcnt(0)
	v_add_f32_e32 v24, v24, v25
	global_atomic_add_f32 v[8:9], v24, off
	s_branch .LBB0_539

.LBB0_595:
	v_add_u32_e32 v26, s0, v31
	v_ashrrev_i32_e32 v27, 31, v26
	v_lshlrev_b64 v[26:27], 12, v[26:27]
	v_lshl_add_u64 v[28:29], v[4:5], 0, v[26:27]
	v_add_co_u32_e32 v26, vcc, 0x4000, v28
	s_nop 1
	v_addc_co_u32_e32 v27, vcc, 0, v29, vcc
	global_load_dwordx4 v[96:99], v[28:29], off
	global_load_dwordx4 v[100:103], v[0:1], off
	global_load_dwordx4 v[104:107], v[2:3], off
	global_load_dwordx4 v[108:111], v[26:27], off
	global_load_dwordx4 v[112:115], v[28:29], off offset:64
	global_load_dwordx4 v[116:119], v[6:7], off
	global_load_dwordx4 v[120:123], v[0:1], off offset:64
	global_load_dwordx4 v[124:127], v[26:27], off offset:64
	global_load_dwordx4 v[128:131], v[28:29], off offset:128
	global_load_dwordx4 v[132:135], v[0:1], off offset:128
	global_load_dwordx4 v[136:139], v[8:9], off
	global_load_dwordx4 v[140:143], v[26:27], off offset:128
	global_load_dwordx4 v[144:147], v[28:29], off offset:192
	global_load_dwordx4 v[148:151], v[0:1], off offset:192
	global_load_dwordx4 v[152:155], v[10:11], off
	global_load_dwordx4 v[156:159], v[26:27], off offset:192
	global_load_dwordx4 v[160:163], v[28:29], off offset:256
	global_load_dwordx4 v[164:167], v[0:1], off offset:256
	global_load_dwordx4 v[168:171], v[12:13], off
	global_load_dwordx4 v[172:175], v[26:27], off offset:256
	global_load_dwordx4 v[176:179], v[28:29], off offset:320
	global_load_dwordx4 v[180:183], v[0:1], off offset:320
	global_load_dwordx4 v[184:187], v[14:15], off
	global_load_dwordx4 v[196:199], v[26:27], off offset:320
	global_load_dwordx4 v[200:203], v[28:29], off offset:384
	global_load_dwordx4 v[204:207], v[0:1], off offset:384
	global_load_dwordx4 v[208:211], v[16:17], off
	global_load_dwordx4 v[212:215], v[26:27], off offset:384
	global_load_dwordx4 v[216:219], v[28:29], off offset:448
	global_load_dwordx4 v[220:223], v[26:27], off offset:448
	global_load_dwordx4 v[224:227], v[0:1], off offset:448
	global_load_dwordx4 v[228:231], v[18:19], off
	s_waitcnt vmcnt(30)
	v_mfma_f32_16x16x32_bf16 v[46:49], v[96:99], v[100:103], 0
	s_waitcnt vmcnt(29)
	v_mfma_f32_16x16x32_bf16 v[34:37], v[96:99], v[104:107], 0
	s_waitcnt vmcnt(28)
	v_mfma_f32_16x16x32_bf16 v[38:41], v[108:111], v[100:103], 0
	v_mfma_f32_16x16x32_bf16 v[42:45], v[108:111], v[104:107], 0
	s_waitcnt vmcnt(25)
	v_mfma_f32_16x16x32_bf16 v[46:49], v[112:115], v[120:123], v[46:49]
	v_mfma_f32_16x16x32_bf16 v[34:37], v[112:115], v[116:119], v[34:37]
	s_waitcnt vmcnt(24)
	v_mfma_f32_16x16x32_bf16 v[38:41], v[124:127], v[120:123], v[38:41]
	v_mfma_f32_16x16x32_bf16 v[42:45], v[124:127], v[116:119], v[42:45]
	s_waitcnt vmcnt(22)
	v_mfma_f32_16x16x32_bf16 v[46:49], v[128:131], v[132:135], v[46:49]
	s_waitcnt vmcnt(21)
	v_mfma_f32_16x16x32_bf16 v[34:37], v[128:131], v[136:139], v[34:37]
	s_waitcnt vmcnt(20)
	v_mfma_f32_16x16x32_bf16 v[38:41], v[140:143], v[132:135], v[38:41]
	v_mfma_f32_16x16x32_bf16 v[42:45], v[140:143], v[136:139], v[42:45]
	s_waitcnt vmcnt(18)
	v_mfma_f32_16x16x32_bf16 v[46:49], v[144:147], v[148:151], v[46:49]
	s_waitcnt vmcnt(17)
	v_mfma_f32_16x16x32_bf16 v[34:37], v[144:147], v[152:155], v[34:37]
	s_waitcnt vmcnt(16)
	v_mfma_f32_16x16x32_bf16 v[38:41], v[156:159], v[148:151], v[38:41]
	v_mfma_f32_16x16x32_bf16 v[42:45], v[156:159], v[152:155], v[42:45]
	s_waitcnt vmcnt(14)
	v_mfma_f32_16x16x32_bf16 v[46:49], v[160:163], v[164:167], v[46:49]
	s_waitcnt vmcnt(13)
	v_mfma_f32_16x16x32_bf16 v[34:37], v[160:163], v[168:171], v[34:37]
	s_waitcnt vmcnt(12)
	v_mfma_f32_16x16x32_bf16 v[38:41], v[172:175], v[164:167], v[38:41]
	v_mfma_f32_16x16x32_bf16 v[42:45], v[172:175], v[168:171], v[42:45]
	s_waitcnt vmcnt(10)
	v_mfma_f32_16x16x32_bf16 v[46:49], v[176:179], v[180:183], v[46:49]
	s_waitcnt vmcnt(9)
	v_mfma_f32_16x16x32_bf16 v[34:37], v[176:179], v[184:187], v[34:37]
	s_waitcnt vmcnt(8)
	v_mfma_f32_16x16x32_bf16 v[38:41], v[196:199], v[180:183], v[38:41]
	v_mfma_f32_16x16x32_bf16 v[42:45], v[196:199], v[184:187], v[42:45]
	s_waitcnt vmcnt(6)
	v_mfma_f32_16x16x32_bf16 v[46:49], v[200:203], v[204:207], v[46:49]
	s_waitcnt vmcnt(5)
	v_mfma_f32_16x16x32_bf16 v[34:37], v[200:203], v[208:211], v[34:37]
	s_waitcnt vmcnt(4)
	v_mfma_f32_16x16x32_bf16 v[38:41], v[212:215], v[204:207], v[38:41]
	v_mfma_f32_16x16x32_bf16 v[42:45], v[212:215], v[208:211], v[42:45]
	s_waitcnt vmcnt(1)
	v_mfma_f32_16x16x32_bf16 v[46:49], v[216:219], v[224:227], v[46:49]
	v_mfma_f32_16x16x32_bf16 v[38:41], v[220:223], v[224:227], v[38:41]
	s_waitcnt vmcnt(0)
	v_mfma_f32_16x16x32_bf16 v[26:29], v[220:223], v[228:231], v[42:45]
	v_mfma_f32_16x16x32_bf16 v[34:37], v[216:219], v[228:231], v[34:37]
	s_nop 7
	s_nop 1
	ds_write_b128 v32, v[46:49]
	s_nop 3
	ds_write_b128 v32, v[34:37] offset:2048
	ds_write_b128 v32, v[38:41] offset:1024
	ds_write_b128 v32, v[26:29] offset:3072
	s_waitcnt lgkmcnt(0)
	s_barrier
	s_and_saveexec_b64 s[10:11], s[6:7]
	s_cbranch_execz .LBB0_594
	ds_read_b128 v[26:29], v33
	ds_read_b128 v[34:37], v33 offset:1024
	ds_read_b128 v[38:41], v33 offset:4096
	v_add_u32_e32 v46, s0, v30
	v_ashrrev_i32_e32 v47, 31, v46
	s_waitcnt lgkmcnt(0)
	v_pk_add_f32 v[40:41], v[28:29], v[40:41]
	v_pk_add_f32 v[38:39], v[26:27], v[38:39]
	ds_read_b128 v[26:29], v33 offset:5120
	s_waitcnt lgkmcnt(0)
	v_pk_add_f32 v[36:37], v[36:37], v[28:29]
	v_pk_add_f32 v[34:35], v[34:35], v[26:27]
	ds_read_b128 v[26:29], v33 offset:8192
	s_waitcnt lgkmcnt(0)
	v_pk_add_f32 v[40:41], v[40:41], v[28:29]
	v_pk_add_f32 v[38:39], v[38:39], v[26:27]
	ds_read_b128 v[26:29], v33 offset:9216
	s_waitcnt lgkmcnt(0)
	v_pk_add_f32 v[36:37], v[36:37], v[28:29]
	v_pk_add_f32 v[34:35], v[34:35], v[26:27]
	ds_read_b128 v[26:29], v33 offset:12288
	s_waitcnt lgkmcnt(0)
	v_pk_add_f32 v[40:41], v[40:41], v[28:29]
	v_pk_add_f32 v[38:39], v[38:39], v[26:27]
	ds_read_b128 v[26:29], v33 offset:13312
	s_waitcnt lgkmcnt(0)
	v_pk_add_f32 v[36:37], v[36:37], v[28:29]
	v_pk_add_f32 v[34:35], v[34:35], v[26:27]
	ds_read_b128 v[26:29], v33 offset:16384
	s_waitcnt lgkmcnt(0)
	v_pk_add_f32 v[40:41], v[40:41], v[28:29]
	v_pk_add_f32 v[38:39], v[38:39], v[26:27]
	ds_read_b128 v[26:29], v33 offset:17408
	s_waitcnt lgkmcnt(0)
	v_pk_add_f32 v[36:37], v[36:37], v[28:29]
	v_pk_add_f32 v[34:35], v[34:35], v[26:27]
	ds_read_b128 v[26:29], v33 offset:20480
	s_waitcnt lgkmcnt(0)
	v_pk_add_f32 v[40:41], v[40:41], v[28:29]
	v_pk_add_f32 v[38:39], v[38:39], v[26:27]
	ds_read_b128 v[26:29], v33 offset:21504
	s_waitcnt lgkmcnt(0)
	v_pk_add_f32 v[36:37], v[36:37], v[28:29]
	v_pk_add_f32 v[34:35], v[34:35], v[26:27]
	ds_read_b128 v[26:29], v33 offset:24576
	s_waitcnt lgkmcnt(0)
	v_pk_add_f32 v[40:41], v[40:41], v[28:29]
	v_pk_add_f32 v[38:39], v[38:39], v[26:27]
	ds_read_b128 v[26:29], v33 offset:25600
	s_waitcnt lgkmcnt(0)
	v_pk_add_f32 v[36:37], v[36:37], v[28:29]
	v_pk_add_f32 v[34:35], v[34:35], v[26:27]
	ds_read_b128 v[26:29], v33 offset:28672
	s_waitcnt lgkmcnt(0)
	v_pk_add_f32 v[40:41], v[40:41], v[28:29]
	v_pk_add_f32 v[38:39], v[38:39], v[26:27]
	ds_read_b128 v[26:29], v33 offset:29696
	s_waitcnt lgkmcnt(0)
	v_pk_add_f32 v[44:45], v[34:35], v[26:27]
	v_lshl_add_u64 v[34:35], v[46:47], 2, v[20:21]
	v_pk_add_f32 v[42:43], v[36:37], v[28:29]
	global_load_dwordx4 v[26:29], v[34:35], off offset:16
	s_nop 0
	global_load_dwordx4 v[34:37], v[34:35], off
	s_waitcnt vmcnt(0)
	v_pk_add_f32 v[36:37], v[40:41], v[36:37]
	v_pk_add_f32 v[34:35], v[38:39], v[34:35]
	v_pk_add_f32 v[38:39], v[42:43], v[28:29]
	v_pk_add_f32 v[40:41], v[44:45], v[26:27]
	v_cvt_pk_bf16_f32 v26, v34, v35
	v_cvt_pk_bf16_f32 v27, v36, v37
	v_lshl_add_u64 v[42:43], v[46:47], 1, v[22:23]
	v_cvt_pk_bf16_f32 v28, v40, v41
	v_cvt_pk_bf16_f32 v29, v38, v39
	global_store_dwordx4 v[42:43], v[26:29], off
	s_nop 1
	v_mul_f32_e32 v26, v35, v35
	v_mul_f32_e32 v27, v37, v37
	v_fmac_f32_e32 v26, v34, v34
	v_fmac_f32_e32 v27, v36, v36
	v_add_f32_e32 v26, v26, v27
	v_mul_f32_e32 v27, v41, v41
	v_mul_f32_e32 v28, v39, v39
	v_fmac_f32_e32 v27, v40, v40
	v_fmac_f32_e32 v28, v38, v38
	v_add_f32_e32 v27, v27, v28
	v_and_b32_e32 v28, 64, v238
	v_add_f32_e32 v26, v26, v27
	v_xor_b32_e32 v27, 16, v238
	v_add_u32_e32 v28, 64, v28
	v_cmp_lt_i32_e32 vcc, v27, v28
	s_nop 1
	v_cndmask_b32_e32 v27, v238, v27, vcc
	v_lshlrev_b32_e32 v27, 2, v27
	ds_bpermute_b32 v27, v27, v26
	s_waitcnt lgkmcnt(0)
	v_add_f32_e32 v26, v26, v27
	v_xor_b32_e32 v27, 32, v238
	v_cmp_lt_i32_e32 vcc, v27, v28
	s_nop 1
	v_cndmask_b32_e32 v27, v238, v27, vcc
	v_lshlrev_b32_e32 v27, 2, v27
	ds_bpermute_b32 v27, v27, v26
	s_and_b64 exec, exec, s[8:9]
	s_cbranch_execz .LBB0_594
	s_waitcnt lgkmcnt(0)
	v_add_f32_e32 v26, v26, v27
	global_atomic_add_f32 v[24:25], v26, off
	s_branch .LBB0_594

.LBB0_1006:
	v_add_u32_e32 v0, s16, v46
	v_ashrrev_i32_e32 v1, 31, v0
	v_lshlrev_b64 v[0:1], 12, v[0:1]
	v_lshl_add_u64 v[2:3], v[14:15], 0, v[0:1]
	v_add_co_u32_e32 v0, vcc, 0x4000, v2
	s_nop 1
	v_addc_co_u32_e32 v1, vcc, 0, v3, vcc
	global_load_dwordx4 v[96:99], v[2:3], off
	global_load_dwordx4 v[100:103], v[10:11], off
	global_load_dwordx4 v[104:107], v[12:13], off
	global_load_dwordx4 v[108:111], v[0:1], off
	global_load_dwordx4 v[112:115], v[2:3], off offset:64
	global_load_dwordx4 v[116:119], v[20:21], off
	global_load_dwordx4 v[120:123], v[10:11], off offset:64
	global_load_dwordx4 v[124:127], v[0:1], off offset:64
	global_load_dwordx4 v[128:131], v[2:3], off offset:128
	global_load_dwordx4 v[132:135], v[10:11], off offset:128
	global_load_dwordx4 v[136:139], v[22:23], off
	global_load_dwordx4 v[140:143], v[0:1], off offset:128
	global_load_dwordx4 v[144:147], v[2:3], off offset:192
	global_load_dwordx4 v[148:151], v[10:11], off offset:192
	global_load_dwordx4 v[152:155], v[24:25], off
	global_load_dwordx4 v[156:159], v[0:1], off offset:192
	global_load_dwordx4 v[160:163], v[2:3], off offset:256
	global_load_dwordx4 v[164:167], v[10:11], off offset:256
	global_load_dwordx4 v[168:171], v[26:27], off
	global_load_dwordx4 v[172:175], v[0:1], off offset:256
	global_load_dwordx4 v[176:179], v[2:3], off offset:320
	global_load_dwordx4 v[180:183], v[10:11], off offset:320
	global_load_dwordx4 v[184:187], v[28:29], off
	global_load_dwordx4 v[196:199], v[0:1], off offset:320
	global_load_dwordx4 v[200:203], v[2:3], off offset:384
	global_load_dwordx4 v[204:207], v[10:11], off offset:384
	global_load_dwordx4 v[208:211], v[30:31], off
	global_load_dwordx4 v[212:215], v[0:1], off offset:384
	global_load_dwordx4 v[216:219], v[2:3], off offset:448
	global_load_dwordx4 v[220:223], v[0:1], off offset:448
	global_load_dwordx4 v[224:227], v[10:11], off offset:448
	global_load_dwordx4 v[228:231], v[32:33], off
	s_waitcnt vmcnt(30)
	v_mfma_f32_16x16x32_bf16 v[58:61], v[96:99], v[100:103], 0
	s_waitcnt vmcnt(29)
	v_mfma_f32_16x16x32_bf16 v[4:7], v[96:99], v[104:107], 0
	s_waitcnt vmcnt(28)
	v_mfma_f32_16x16x32_bf16 v[50:53], v[108:111], v[100:103], 0
	v_mfma_f32_16x16x32_bf16 v[54:57], v[108:111], v[104:107], 0
	s_waitcnt vmcnt(25)
	v_mfma_f32_16x16x32_bf16 v[58:61], v[112:115], v[120:123], v[58:61]
	v_mfma_f32_16x16x32_bf16 v[4:7], v[112:115], v[116:119], v[4:7]
	s_waitcnt vmcnt(24)
	v_mfma_f32_16x16x32_bf16 v[50:53], v[124:127], v[120:123], v[50:53]
	v_mfma_f32_16x16x32_bf16 v[54:57], v[124:127], v[116:119], v[54:57]
	s_waitcnt vmcnt(22)
	v_mfma_f32_16x16x32_bf16 v[58:61], v[128:131], v[132:135], v[58:61]
	s_waitcnt vmcnt(21)
	v_mfma_f32_16x16x32_bf16 v[4:7], v[128:131], v[136:139], v[4:7]
	s_waitcnt vmcnt(20)
	v_mfma_f32_16x16x32_bf16 v[50:53], v[140:143], v[132:135], v[50:53]
	v_mfma_f32_16x16x32_bf16 v[54:57], v[140:143], v[136:139], v[54:57]
	s_waitcnt vmcnt(18)
	v_mfma_f32_16x16x32_bf16 v[58:61], v[144:147], v[148:151], v[58:61]
	s_waitcnt vmcnt(17)
	v_mfma_f32_16x16x32_bf16 v[4:7], v[144:147], v[152:155], v[4:7]
	s_waitcnt vmcnt(16)
	v_mfma_f32_16x16x32_bf16 v[50:53], v[156:159], v[148:151], v[50:53]
	v_mfma_f32_16x16x32_bf16 v[54:57], v[156:159], v[152:155], v[54:57]
	s_waitcnt vmcnt(14)
	v_mfma_f32_16x16x32_bf16 v[58:61], v[160:163], v[164:167], v[58:61]
	s_waitcnt vmcnt(13)
	v_mfma_f32_16x16x32_bf16 v[4:7], v[160:163], v[168:171], v[4:7]
	s_waitcnt vmcnt(12)
	v_mfma_f32_16x16x32_bf16 v[50:53], v[172:175], v[164:167], v[50:53]
	v_mfma_f32_16x16x32_bf16 v[54:57], v[172:175], v[168:171], v[54:57]
	s_waitcnt vmcnt(10)
	v_mfma_f32_16x16x32_bf16 v[58:61], v[176:179], v[180:183], v[58:61]
	s_waitcnt vmcnt(9)
	v_mfma_f32_16x16x32_bf16 v[4:7], v[176:179], v[184:187], v[4:7]
	s_waitcnt vmcnt(8)
	v_mfma_f32_16x16x32_bf16 v[50:53], v[196:199], v[180:183], v[50:53]
	v_mfma_f32_16x16x32_bf16 v[54:57], v[196:199], v[184:187], v[54:57]
	s_waitcnt vmcnt(6)
	v_mfma_f32_16x16x32_bf16 v[58:61], v[200:203], v[204:207], v[58:61]
	s_waitcnt vmcnt(5)
	v_mfma_f32_16x16x32_bf16 v[4:7], v[200:203], v[208:211], v[4:7]
	s_waitcnt vmcnt(4)
	v_mfma_f32_16x16x32_bf16 v[50:53], v[212:215], v[204:207], v[50:53]
	v_mfma_f32_16x16x32_bf16 v[54:57], v[212:215], v[208:211], v[54:57]
	s_waitcnt vmcnt(1)
	v_mfma_f32_16x16x32_bf16 v[58:61], v[216:219], v[224:227], v[58:61]
	v_mfma_f32_16x16x32_bf16 v[50:53], v[220:223], v[224:227], v[50:53]
	s_waitcnt vmcnt(0)
	v_mfma_f32_16x16x32_bf16 v[0:3], v[220:223], v[228:231], v[54:57]
	v_mfma_f32_16x16x32_bf16 v[4:7], v[216:219], v[228:231], v[4:7]
	s_nop 7
	s_nop 1
	ds_write_b128 v47, v[58:61]
	s_nop 3
	ds_write_b128 v47, v[4:7] offset:2048
	ds_write_b128 v47, v[50:53] offset:1024
	ds_write_b128 v47, v[0:3] offset:3072
	s_waitcnt lgkmcnt(0)
	s_barrier
	s_and_saveexec_b64 s[12:13], s[4:5]
	s_cbranch_execz .LBB0_1005
	ds_read_b128 v[0:3], v48
	ds_read_b128 v[4:7], v48 offset:1024
	ds_read_b128 v[50:53], v48 offset:4096
	s_ashr_i32 s14, s17, 6
	v_add_u32_e32 v49, s16, v44
	s_add_i32 s0, s14, -1
	s_cmp_gt_u32 s0, 1
	s_waitcnt lgkmcnt(0)
	v_pk_add_f32 v[8:9], v[2:3], v[52:53]
	v_pk_add_f32 v[42:43], v[0:1], v[50:51]
	ds_read_b128 v[0:3], v48 offset:5120
	s_waitcnt lgkmcnt(0)
	v_pk_add_f32 v[6:7], v[6:7], v[2:3]
	v_pk_add_f32 v[4:5], v[4:5], v[0:1]
	ds_read_b128 v[0:3], v48 offset:8192
	s_waitcnt lgkmcnt(0)
	v_pk_add_f32 v[8:9], v[8:9], v[2:3]
	v_pk_add_f32 v[42:43], v[42:43], v[0:1]
	ds_read_b128 v[0:3], v48 offset:9216
	s_waitcnt lgkmcnt(0)
	v_pk_add_f32 v[6:7], v[6:7], v[2:3]
	v_pk_add_f32 v[4:5], v[4:5], v[0:1]
	ds_read_b128 v[0:3], v48 offset:12288
	s_waitcnt lgkmcnt(0)
	v_pk_add_f32 v[8:9], v[8:9], v[2:3]
	v_pk_add_f32 v[42:43], v[42:43], v[0:1]
	ds_read_b128 v[0:3], v48 offset:13312
	s_waitcnt lgkmcnt(0)
	v_pk_add_f32 v[6:7], v[6:7], v[2:3]
	v_pk_add_f32 v[4:5], v[4:5], v[0:1]
	ds_read_b128 v[0:3], v48 offset:16384
	s_waitcnt lgkmcnt(0)
	v_pk_add_f32 v[8:9], v[8:9], v[2:3]
	v_pk_add_f32 v[42:43], v[42:43], v[0:1]
	ds_read_b128 v[0:3], v48 offset:17408
	s_waitcnt lgkmcnt(0)
	v_pk_add_f32 v[6:7], v[6:7], v[2:3]
	v_pk_add_f32 v[4:5], v[4:5], v[0:1]
	ds_read_b128 v[0:3], v48 offset:20480
	s_waitcnt lgkmcnt(0)
	v_pk_add_f32 v[8:9], v[8:9], v[2:3]
	v_pk_add_f32 v[42:43], v[42:43], v[0:1]
	ds_read_b128 v[0:3], v48 offset:21504
	s_waitcnt lgkmcnt(0)
	v_pk_add_f32 v[6:7], v[6:7], v[2:3]
	v_pk_add_f32 v[4:5], v[4:5], v[0:1]
	ds_read_b128 v[0:3], v48 offset:24576
	s_waitcnt lgkmcnt(0)
	v_pk_add_f32 v[8:9], v[8:9], v[2:3]
	v_pk_add_f32 v[42:43], v[42:43], v[0:1]
	ds_read_b128 v[0:3], v48 offset:25600
	s_waitcnt lgkmcnt(0)
	v_pk_add_f32 v[50:51], v[6:7], v[2:3]
	v_pk_add_f32 v[52:53], v[4:5], v[0:1]
	ds_read_b128 v[2:5], v48 offset:28672
	s_waitcnt lgkmcnt(0)
	v_pk_add_f32 v[0:1], v[8:9], v[4:5]
	ds_read_b128 v[6:9], v48 offset:29696
	v_pk_add_f32 v[4:5], v[42:43], v[2:3]
	s_waitcnt lgkmcnt(0)
	v_pk_add_f32 v[42:43], v[52:53], v[6:7]
	global_load_dword v6, v[34:35], off
	v_pk_add_f32 v[2:3], v[50:51], v[8:9]
	s_waitcnt vmcnt(0)
	v_fmamk_f32 v6, v6, 0x3a000000, v233
	v_cmp_gt_f32_e32 vcc, s96, v6
	v_mul_f32_e32 v7, 0x4b800000, v6
	s_nop 0
	v_cndmask_b32_e32 v6, v6, v7, vcc
	v_rsq_f32_e32 v6, v6
	s_nop 0
	v_mul_f32_e32 v7, 0x45800000, v6
	v_cndmask_b32_e32 v50, v6, v7, vcc
	v_pk_mul_f32 v[6:7], v[4:5], v[50:51] op_sel_hi:[1,0]
	v_pk_mul_f32 v[8:9], v[0:1], v[50:51] op_sel_hi:[1,0]
	v_pk_mul_f32 v[0:1], v[42:43], v[50:51] op_sel_hi:[1,0]
	v_pk_mul_f32 v[2:3], v[2:3], v[50:51] op_sel_hi:[1,0]
	v_and_b32_e32 v42, 0x7f8, v49
	s_cbranch_scc1 .LBB0_1013
	s_cmp_eq_u32 s14, 1
	s_cselect_b64 s[0:1], -1, 0
	v_lshlrev_b32_e32 v188, 2, v42
	s_and_saveexec_b64 s[2:3], s[6:7]
	s_xor_b64 s[2:3], exec, s[2:3]
	s_cbranch_execnz .LBB0_1025
	s_andn2_saveexec_b64 s[2:3], s[2:3]
	s_cbranch_execnz .LBB0_1026

.LBB0_1309:
	v_add_u32_e32 v26, s0, v31
	v_ashrrev_i32_e32 v27, 31, v26
	v_lshlrev_b64 v[26:27], 12, v[26:27]
	v_lshl_add_u64 v[28:29], v[4:5], 0, v[26:27]
	v_add_co_u32_e32 v26, vcc, 0x4000, v28
	s_nop 1
	v_addc_co_u32_e32 v27, vcc, 0, v29, vcc
	global_load_dwordx4 v[96:99], v[28:29], off
	global_load_dwordx4 v[100:103], v[0:1], off
	global_load_dwordx4 v[104:107], v[2:3], off
	global_load_dwordx4 v[108:111], v[26:27], off
	global_load_dwordx4 v[112:115], v[28:29], off offset:64
	global_load_dwordx4 v[116:119], v[6:7], off
	global_load_dwordx4 v[120:123], v[0:1], off offset:64
	global_load_dwordx4 v[124:127], v[26:27], off offset:64
	global_load_dwordx4 v[128:131], v[28:29], off offset:128
	global_load_dwordx4 v[132:135], v[0:1], off offset:128
	global_load_dwordx4 v[136:139], v[8:9], off
	global_load_dwordx4 v[140:143], v[26:27], off offset:128
	global_load_dwordx4 v[144:147], v[28:29], off offset:192
	global_load_dwordx4 v[148:151], v[0:1], off offset:192
	global_load_dwordx4 v[152:155], v[10:11], off
	global_load_dwordx4 v[156:159], v[26:27], off offset:192
	global_load_dwordx4 v[160:163], v[28:29], off offset:256
	global_load_dwordx4 v[164:167], v[0:1], off offset:256
	global_load_dwordx4 v[168:171], v[12:13], off
	global_load_dwordx4 v[172:175], v[26:27], off offset:256
	global_load_dwordx4 v[176:179], v[28:29], off offset:320
	global_load_dwordx4 v[180:183], v[0:1], off offset:320
	global_load_dwordx4 v[184:187], v[14:15], off
	global_load_dwordx4 v[196:199], v[26:27], off offset:320
	global_load_dwordx4 v[200:203], v[28:29], off offset:384
	global_load_dwordx4 v[204:207], v[0:1], off offset:384
	global_load_dwordx4 v[208:211], v[16:17], off
	global_load_dwordx4 v[212:215], v[26:27], off offset:384
	global_load_dwordx4 v[216:219], v[28:29], off offset:448
	global_load_dwordx4 v[220:223], v[26:27], off offset:448
	global_load_dwordx4 v[224:227], v[0:1], off offset:448
	global_load_dwordx4 v[228:231], v[18:19], off
	s_waitcnt vmcnt(30)
	v_mfma_f32_16x16x32_bf16 v[46:49], v[96:99], v[100:103], 0
	s_waitcnt vmcnt(29)
	v_mfma_f32_16x16x32_bf16 v[34:37], v[96:99], v[104:107], 0
	s_waitcnt vmcnt(28)
	v_mfma_f32_16x16x32_bf16 v[38:41], v[108:111], v[100:103], 0
	v_mfma_f32_16x16x32_bf16 v[42:45], v[108:111], v[104:107], 0
	s_waitcnt vmcnt(25)
	v_mfma_f32_16x16x32_bf16 v[46:49], v[112:115], v[120:123], v[46:49]
	v_mfma_f32_16x16x32_bf16 v[34:37], v[112:115], v[116:119], v[34:37]
	s_waitcnt vmcnt(24)
	v_mfma_f32_16x16x32_bf16 v[38:41], v[124:127], v[120:123], v[38:41]
	v_mfma_f32_16x16x32_bf16 v[42:45], v[124:127], v[116:119], v[42:45]
	s_waitcnt vmcnt(22)
	v_mfma_f32_16x16x32_bf16 v[46:49], v[128:131], v[132:135], v[46:49]
	s_waitcnt vmcnt(21)
	v_mfma_f32_16x16x32_bf16 v[34:37], v[128:131], v[136:139], v[34:37]
	s_waitcnt vmcnt(20)
	v_mfma_f32_16x16x32_bf16 v[38:41], v[140:143], v[132:135], v[38:41]
	v_mfma_f32_16x16x32_bf16 v[42:45], v[140:143], v[136:139], v[42:45]
	s_waitcnt vmcnt(18)
	v_mfma_f32_16x16x32_bf16 v[46:49], v[144:147], v[148:151], v[46:49]
	s_waitcnt vmcnt(17)
	v_mfma_f32_16x16x32_bf16 v[34:37], v[144:147], v[152:155], v[34:37]
	s_waitcnt vmcnt(16)
	v_mfma_f32_16x16x32_bf16 v[38:41], v[156:159], v[148:151], v[38:41]
	v_mfma_f32_16x16x32_bf16 v[42:45], v[156:159], v[152:155], v[42:45]
	s_waitcnt vmcnt(14)
	v_mfma_f32_16x16x32_bf16 v[46:49], v[160:163], v[164:167], v[46:49]
	s_waitcnt vmcnt(13)
	v_mfma_f32_16x16x32_bf16 v[34:37], v[160:163], v[168:171], v[34:37]
	s_waitcnt vmcnt(12)
	v_mfma_f32_16x16x32_bf16 v[38:41], v[172:175], v[164:167], v[38:41]
	v_mfma_f32_16x16x32_bf16 v[42:45], v[172:175], v[168:171], v[42:45]
	s_waitcnt vmcnt(10)
	v_mfma_f32_16x16x32_bf16 v[46:49], v[176:179], v[180:183], v[46:49]
	s_waitcnt vmcnt(9)
	v_mfma_f32_16x16x32_bf16 v[34:37], v[176:179], v[184:187], v[34:37]
	s_waitcnt vmcnt(8)
	v_mfma_f32_16x16x32_bf16 v[38:41], v[196:199], v[180:183], v[38:41]
	v_mfma_f32_16x16x32_bf16 v[42:45], v[196:199], v[184:187], v[42:45]
	s_waitcnt vmcnt(6)
	v_mfma_f32_16x16x32_bf16 v[46:49], v[200:203], v[204:207], v[46:49]
	s_waitcnt vmcnt(5)
	v_mfma_f32_16x16x32_bf16 v[34:37], v[200:203], v[208:211], v[34:37]
	s_waitcnt vmcnt(4)
	v_mfma_f32_16x16x32_bf16 v[38:41], v[212:215], v[204:207], v[38:41]
	v_mfma_f32_16x16x32_bf16 v[42:45], v[212:215], v[208:211], v[42:45]
	s_waitcnt vmcnt(1)
	v_mfma_f32_16x16x32_bf16 v[46:49], v[216:219], v[224:227], v[46:49]
	v_mfma_f32_16x16x32_bf16 v[38:41], v[220:223], v[224:227], v[38:41]
	s_waitcnt vmcnt(0)
	v_mfma_f32_16x16x32_bf16 v[26:29], v[220:223], v[228:231], v[42:45]
	v_mfma_f32_16x16x32_bf16 v[34:37], v[216:219], v[228:231], v[34:37]
	s_nop 7
	s_nop 1
	ds_write_b128 v32, v[46:49]
	s_nop 3
	ds_write_b128 v32, v[34:37] offset:2048
	ds_write_b128 v32, v[38:41] offset:1024
	ds_write_b128 v32, v[26:29] offset:3072
	s_waitcnt lgkmcnt(0)
	s_barrier
	s_and_saveexec_b64 s[8:9], s[4:5]
	s_cbranch_execz .LBB0_1308
	ds_read_b128 v[26:29], v33
	ds_read_b128 v[34:37], v33 offset:1024
	ds_read_b128 v[38:41], v33 offset:4096
	v_add_u32_e32 v42, s0, v30
	v_ashrrev_i32_e32 v43, 31, v42
	s_waitcnt lgkmcnt(0)
	v_pk_add_f32 v[40:41], v[28:29], v[40:41]
	v_pk_add_f32 v[38:39], v[26:27], v[38:39]
	ds_read_b128 v[26:29], v33 offset:5120
	s_waitcnt lgkmcnt(0)
	v_pk_add_f32 v[36:37], v[36:37], v[28:29]
	v_pk_add_f32 v[34:35], v[34:35], v[26:27]
	ds_read_b128 v[26:29], v33 offset:8192
	s_waitcnt lgkmcnt(0)
	v_pk_add_f32 v[40:41], v[40:41], v[28:29]
	v_pk_add_f32 v[38:39], v[38:39], v[26:27]
	ds_read_b128 v[26:29], v33 offset:9216
	s_waitcnt lgkmcnt(0)
	v_pk_add_f32 v[36:37], v[36:37], v[28:29]
	v_pk_add_f32 v[34:35], v[34:35], v[26:27]
	ds_read_b128 v[26:29], v33 offset:12288
	s_waitcnt lgkmcnt(0)
	v_pk_add_f32 v[40:41], v[40:41], v[28:29]
	v_pk_add_f32 v[38:39], v[38:39], v[26:27]
	ds_read_b128 v[26:29], v33 offset:13312
	s_waitcnt lgkmcnt(0)
	v_pk_add_f32 v[36:37], v[36:37], v[28:29]
	v_pk_add_f32 v[34:35], v[34:35], v[26:27]
	ds_read_b128 v[26:29], v33 offset:16384
	s_waitcnt lgkmcnt(0)
	v_pk_add_f32 v[40:41], v[40:41], v[28:29]
	v_pk_add_f32 v[38:39], v[38:39], v[26:27]
	ds_read_b128 v[26:29], v33 offset:17408
	s_waitcnt lgkmcnt(0)
	v_pk_add_f32 v[36:37], v[36:37], v[28:29]
	v_pk_add_f32 v[34:35], v[34:35], v[26:27]
	ds_read_b128 v[26:29], v33 offset:20480
	s_waitcnt lgkmcnt(0)
	v_pk_add_f32 v[40:41], v[40:41], v[28:29]
	v_pk_add_f32 v[38:39], v[38:39], v[26:27]
	ds_read_b128 v[26:29], v33 offset:21504
	s_waitcnt lgkmcnt(0)
	v_pk_add_f32 v[36:37], v[36:37], v[28:29]
	v_pk_add_f32 v[34:35], v[34:35], v[26:27]
	ds_read_b128 v[26:29], v33 offset:24576
	s_waitcnt lgkmcnt(0)
	v_pk_add_f32 v[40:41], v[40:41], v[28:29]
	v_pk_add_f32 v[38:39], v[38:39], v[26:27]
	ds_read_b128 v[26:29], v33 offset:25600
	s_waitcnt lgkmcnt(0)
	v_pk_add_f32 v[36:37], v[36:37], v[28:29]
	v_pk_add_f32 v[34:35], v[34:35], v[26:27]
	ds_read_b128 v[26:29], v33 offset:28672
	s_waitcnt lgkmcnt(0)
	v_pk_add_f32 v[40:41], v[40:41], v[28:29]
	v_pk_add_f32 v[38:39], v[38:39], v[26:27]
	ds_read_b128 v[26:29], v33 offset:29696
	s_waitcnt lgkmcnt(0)
	v_pk_add_f32 v[34:35], v[34:35], v[26:27]
	v_lshl_add_u64 v[26:27], v[42:43], 1, v[20:21]
	v_pk_add_f32 v[36:37], v[36:37], v[28:29]
	global_load_dwordx4 v[26:29], v[26:27], off
	s_waitcnt vmcnt(0)
	v_lshlrev_b32_e32 v44, 16, v26
	v_and_b32_e32 v45, 0xffff0000, v26
	v_lshlrev_b32_e32 v26, 16, v27
	v_and_b32_e32 v27, 0xffff0000, v27
	v_lshlrev_b32_e32 v46, 16, v28
	v_and_b32_e32 v47, 0xffff0000, v28
	v_lshlrev_b32_e32 v48, 16, v29
	v_and_b32_e32 v49, 0xffff0000, v29
	v_pk_add_f32 v[28:29], v[40:41], v[26:27]
	v_pk_add_f32 v[26:27], v[38:39], v[44:45]
	v_lshl_add_u64 v[38:39], v[42:43], 2, v[22:23]
	v_pk_add_f32 v[36:37], v[36:37], v[48:49]
	v_pk_add_f32 v[34:35], v[34:35], v[46:47]
	global_store_dwordx4 v[38:39], v[26:29], off
	global_store_dwordx4 v[38:39], v[34:37], off offset:16
	s_nop 0
	v_mul_f32_e32 v27, v27, v27
	v_fmac_f32_e32 v27, v26, v26
	v_mul_f32_e32 v26, v29, v29
	v_fmac_f32_e32 v26, v28, v28
	v_add_f32_e32 v26, v27, v26
	v_mul_f32_e32 v27, v35, v35
	v_mul_f32_e32 v28, v37, v37
	v_fmac_f32_e32 v27, v34, v34
	v_fmac_f32_e32 v28, v36, v36
	v_add_f32_e32 v27, v27, v28
	v_and_b32_e32 v28, 64, v238
	v_add_f32_e32 v26, v26, v27
	v_xor_b32_e32 v27, 16, v238
	v_add_u32_e32 v28, 64, v28
	v_cmp_lt_i32_e32 vcc, v27, v28
	s_nop 1
	v_cndmask_b32_e32 v27, v238, v27, vcc
	v_lshlrev_b32_e32 v27, 2, v27
	ds_bpermute_b32 v27, v27, v26
	s_waitcnt lgkmcnt(0)
	v_add_f32_e32 v26, v26, v27
	v_xor_b32_e32 v27, 32, v238
	v_cmp_lt_i32_e32 vcc, v27, v28
	s_nop 1
	v_cndmask_b32_e32 v27, v238, v27, vcc
	v_lshlrev_b32_e32 v27, 2, v27
	ds_bpermute_b32 v27, v27, v26
	s_and_b64 exec, exec, s[6:7]
	s_cbranch_execz .LBB0_1308
	s_waitcnt lgkmcnt(0)
	v_add_f32_e32 v26, v26, v27
	global_atomic_add_f32 v[24:25], v26, off
	s_branch .LBB0_1308

.LBB0_1362:
	v_add_u32_e32 v24, s0, v29
	v_ashrrev_i32_e32 v25, 31, v24
	v_lshlrev_b64 v[24:25], 12, v[24:25]
	v_lshl_add_u64 v[26:27], v[4:5], 0, v[24:25]
	v_add_co_u32_e32 v24, vcc, 0x4000, v26
	s_nop 1
	v_addc_co_u32_e32 v25, vcc, 0, v27, vcc
	global_load_dwordx4 v[96:99], v[26:27], off
	global_load_dwordx4 v[100:103], v[0:1], off
	global_load_dwordx4 v[104:107], v[2:3], off
	global_load_dwordx4 v[108:111], v[24:25], off
	global_load_dwordx4 v[112:115], v[26:27], off offset:64
	global_load_dwordx4 v[116:119], v[10:11], off
	global_load_dwordx4 v[120:123], v[0:1], off offset:64
	global_load_dwordx4 v[124:127], v[24:25], off offset:64
	global_load_dwordx4 v[128:131], v[26:27], off offset:128
	global_load_dwordx4 v[132:135], v[0:1], off offset:128
	global_load_dwordx4 v[136:139], v[12:13], off
	global_load_dwordx4 v[140:143], v[24:25], off offset:128
	global_load_dwordx4 v[144:147], v[26:27], off offset:192
	global_load_dwordx4 v[148:151], v[0:1], off offset:192
	global_load_dwordx4 v[152:155], v[14:15], off
	global_load_dwordx4 v[156:159], v[24:25], off offset:192
	global_load_dwordx4 v[160:163], v[26:27], off offset:256
	global_load_dwordx4 v[164:167], v[0:1], off offset:256
	global_load_dwordx4 v[168:171], v[16:17], off
	global_load_dwordx4 v[172:175], v[24:25], off offset:256
	global_load_dwordx4 v[176:179], v[26:27], off offset:320
	global_load_dwordx4 v[180:183], v[0:1], off offset:320
	global_load_dwordx4 v[184:187], v[18:19], off
	global_load_dwordx4 v[196:199], v[24:25], off offset:320
	global_load_dwordx4 v[200:203], v[26:27], off offset:384
	global_load_dwordx4 v[204:207], v[0:1], off offset:384
	global_load_dwordx4 v[208:211], v[20:21], off
	global_load_dwordx4 v[212:215], v[24:25], off offset:384
	global_load_dwordx4 v[216:219], v[26:27], off offset:448
	global_load_dwordx4 v[220:223], v[24:25], off offset:448
	global_load_dwordx4 v[224:227], v[0:1], off offset:448
	global_load_dwordx4 v[228:231], v[22:23], off
	s_waitcnt vmcnt(30)
	v_mfma_f32_16x16x32_bf16 v[44:47], v[96:99], v[100:103], 0
	s_waitcnt vmcnt(29)
	v_mfma_f32_16x16x32_bf16 v[32:35], v[96:99], v[104:107], 0
	s_waitcnt vmcnt(28)
	v_mfma_f32_16x16x32_bf16 v[36:39], v[108:111], v[100:103], 0
	v_mfma_f32_16x16x32_bf16 v[40:43], v[108:111], v[104:107], 0
	s_waitcnt vmcnt(25)
	v_mfma_f32_16x16x32_bf16 v[44:47], v[112:115], v[120:123], v[44:47]
	v_mfma_f32_16x16x32_bf16 v[32:35], v[112:115], v[116:119], v[32:35]
	s_waitcnt vmcnt(24)
	v_mfma_f32_16x16x32_bf16 v[36:39], v[124:127], v[120:123], v[36:39]
	v_mfma_f32_16x16x32_bf16 v[40:43], v[124:127], v[116:119], v[40:43]
	s_waitcnt vmcnt(22)
	v_mfma_f32_16x16x32_bf16 v[44:47], v[128:131], v[132:135], v[44:47]
	s_waitcnt vmcnt(21)
	v_mfma_f32_16x16x32_bf16 v[32:35], v[128:131], v[136:139], v[32:35]
	s_waitcnt vmcnt(20)
	v_mfma_f32_16x16x32_bf16 v[36:39], v[140:143], v[132:135], v[36:39]
	v_mfma_f32_16x16x32_bf16 v[40:43], v[140:143], v[136:139], v[40:43]
	s_waitcnt vmcnt(18)
	v_mfma_f32_16x16x32_bf16 v[44:47], v[144:147], v[148:151], v[44:47]
	s_waitcnt vmcnt(17)
	v_mfma_f32_16x16x32_bf16 v[32:35], v[144:147], v[152:155], v[32:35]
	s_waitcnt vmcnt(16)
	v_mfma_f32_16x16x32_bf16 v[36:39], v[156:159], v[148:151], v[36:39]
	v_mfma_f32_16x16x32_bf16 v[40:43], v[156:159], v[152:155], v[40:43]
	s_waitcnt vmcnt(14)
	v_mfma_f32_16x16x32_bf16 v[44:47], v[160:163], v[164:167], v[44:47]
	s_waitcnt vmcnt(13)
	v_mfma_f32_16x16x32_bf16 v[32:35], v[160:163], v[168:171], v[32:35]
	s_waitcnt vmcnt(12)
	v_mfma_f32_16x16x32_bf16 v[36:39], v[172:175], v[164:167], v[36:39]
	v_mfma_f32_16x16x32_bf16 v[40:43], v[172:175], v[168:171], v[40:43]
	s_waitcnt vmcnt(10)
	v_mfma_f32_16x16x32_bf16 v[44:47], v[176:179], v[180:183], v[44:47]
	s_waitcnt vmcnt(9)
	v_mfma_f32_16x16x32_bf16 v[32:35], v[176:179], v[184:187], v[32:35]
	s_waitcnt vmcnt(8)
	v_mfma_f32_16x16x32_bf16 v[36:39], v[196:199], v[180:183], v[36:39]
	v_mfma_f32_16x16x32_bf16 v[40:43], v[196:199], v[184:187], v[40:43]
	s_waitcnt vmcnt(6)
	v_mfma_f32_16x16x32_bf16 v[44:47], v[200:203], v[204:207], v[44:47]
	s_waitcnt vmcnt(5)
	v_mfma_f32_16x16x32_bf16 v[32:35], v[200:203], v[208:211], v[32:35]
	s_waitcnt vmcnt(4)
	v_mfma_f32_16x16x32_bf16 v[36:39], v[212:215], v[204:207], v[36:39]
	v_mfma_f32_16x16x32_bf16 v[40:43], v[212:215], v[208:211], v[40:43]
	s_waitcnt vmcnt(1)
	v_mfma_f32_16x16x32_bf16 v[44:47], v[216:219], v[224:227], v[44:47]
	v_mfma_f32_16x16x32_bf16 v[36:39], v[220:223], v[224:227], v[36:39]
	s_waitcnt vmcnt(0)
	v_mfma_f32_16x16x32_bf16 v[24:27], v[220:223], v[228:231], v[40:43]
	v_mfma_f32_16x16x32_bf16 v[32:35], v[216:219], v[228:231], v[32:35]
	s_nop 7
	s_nop 1
	ds_write_b128 v30, v[44:47]
	s_nop 3
	ds_write_b128 v30, v[32:35] offset:2048
	ds_write_b128 v30, v[36:39] offset:1024
	ds_write_b128 v30, v[24:27] offset:3072
	s_waitcnt lgkmcnt(0)
	s_barrier
	s_and_saveexec_b64 s[8:9], s[4:5]
	s_cbranch_execz .LBB0_1361
	ds_read_b128 v[24:27], v31
	ds_read_b128 v[32:35], v31 offset:1024
	ds_read_b128 v[36:39], v31 offset:4096
	s_waitcnt lgkmcnt(0)
	v_pk_add_f32 v[38:39], v[26:27], v[38:39]
	v_pk_add_f32 v[36:37], v[24:25], v[36:37]
	ds_read_b128 v[24:27], v31 offset:5120
	s_waitcnt lgkmcnt(0)
	v_pk_add_f32 v[34:35], v[34:35], v[26:27]
	v_pk_add_f32 v[32:33], v[32:33], v[24:25]
	ds_read_b128 v[24:27], v31 offset:8192
	s_waitcnt lgkmcnt(0)
	v_pk_add_f32 v[38:39], v[38:39], v[26:27]
	v_pk_add_f32 v[36:37], v[36:37], v[24:25]
	ds_read_b128 v[24:27], v31 offset:9216
	s_waitcnt lgkmcnt(0)
	v_pk_add_f32 v[34:35], v[34:35], v[26:27]
	v_pk_add_f32 v[32:33], v[32:33], v[24:25]
	ds_read_b128 v[24:27], v31 offset:12288
	s_waitcnt lgkmcnt(0)
	v_pk_add_f32 v[38:39], v[38:39], v[26:27]
	v_pk_add_f32 v[36:37], v[36:37], v[24:25]
	ds_read_b128 v[24:27], v31 offset:13312
	s_waitcnt lgkmcnt(0)
	v_pk_add_f32 v[34:35], v[34:35], v[26:27]
	v_pk_add_f32 v[32:33], v[32:33], v[24:25]
	ds_read_b128 v[24:27], v31 offset:16384
	s_waitcnt lgkmcnt(0)
	v_pk_add_f32 v[38:39], v[38:39], v[26:27]
	v_pk_add_f32 v[36:37], v[36:37], v[24:25]
	ds_read_b128 v[24:27], v31 offset:17408
	s_waitcnt lgkmcnt(0)
	v_pk_add_f32 v[34:35], v[34:35], v[26:27]
	v_pk_add_f32 v[32:33], v[32:33], v[24:25]
	ds_read_b128 v[24:27], v31 offset:20480
	s_waitcnt lgkmcnt(0)
	v_pk_add_f32 v[38:39], v[38:39], v[26:27]
	v_pk_add_f32 v[36:37], v[36:37], v[24:25]
	ds_read_b128 v[24:27], v31 offset:21504
	s_waitcnt lgkmcnt(0)
	v_pk_add_f32 v[34:35], v[34:35], v[26:27]
	v_pk_add_f32 v[32:33], v[32:33], v[24:25]
	ds_read_b128 v[24:27], v31 offset:24576
	s_waitcnt lgkmcnt(0)
	v_pk_add_f32 v[38:39], v[38:39], v[26:27]
	v_pk_add_f32 v[36:37], v[36:37], v[24:25]
	ds_read_b128 v[24:27], v31 offset:25600
	s_waitcnt lgkmcnt(0)
	v_pk_add_f32 v[34:35], v[34:35], v[26:27]
	v_pk_add_f32 v[32:33], v[32:33], v[24:25]
	ds_read_b128 v[24:27], v31 offset:28672
	s_waitcnt lgkmcnt(0)
	v_pk_add_f32 v[38:39], v[38:39], v[26:27]
	v_pk_add_f32 v[36:37], v[36:37], v[24:25]
	ds_read_b128 v[24:27], v31 offset:29696
	s_waitcnt lgkmcnt(0)
	v_pk_add_f32 v[32:33], v[32:33], v[24:25]
	v_add_u32_e32 v24, s0, v28
	v_ashrrev_i32_e32 v25, 31, v24
	v_lshl_add_u64 v[40:41], v[24:25], 1, v[6:7]
	v_pk_add_f32 v[34:35], v[34:35], v[26:27]
	global_load_dwordx4 v[24:27], v[40:41], off
	s_waitcnt vmcnt(0)
	v_lshlrev_b32_e32 v42, 16, v24
	v_and_b32_e32 v43, 0xffff0000, v24
	v_lshlrev_b32_e32 v24, 16, v25
	v_and_b32_e32 v25, 0xffff0000, v25
	v_lshlrev_b32_e32 v44, 16, v26
	v_and_b32_e32 v45, 0xffff0000, v26
	v_lshlrev_b32_e32 v26, 16, v27
	v_and_b32_e32 v27, 0xffff0000, v27
	v_pk_add_f32 v[38:39], v[38:39], v[24:25]
	v_pk_add_f32 v[36:37], v[36:37], v[42:43]
	v_pk_add_f32 v[34:35], v[34:35], v[26:27]
	v_cvt_pk_bf16_f32 v24, v36, v37
	v_cvt_pk_bf16_f32 v25, v38, v39
	v_pk_add_f32 v[32:33], v[32:33], v[44:45]
	s_nop 0
	v_cvt_pk_bf16_f32 v26, v32, v33
	v_cvt_pk_bf16_f32 v27, v34, v35
	global_store_dwordx4 v[40:41], v[24:27], off
	s_nop 1
	v_mul_f32_e32 v24, v37, v37
	v_mul_f32_e32 v25, v39, v39
	v_fmac_f32_e32 v24, v36, v36
	v_fmac_f32_e32 v25, v38, v38
	v_add_f32_e32 v24, v24, v25
	v_mul_f32_e32 v25, v33, v33
	v_mul_f32_e32 v26, v35, v35
	v_fmac_f32_e32 v25, v32, v32
	v_fmac_f32_e32 v26, v34, v34
	v_add_f32_e32 v25, v25, v26
	v_and_b32_e32 v26, 64, v238
	v_add_f32_e32 v24, v24, v25
	v_xor_b32_e32 v25, 16, v238
	v_add_u32_e32 v26, 64, v26
	v_cmp_lt_i32_e32 vcc, v25, v26
	s_nop 1
	v_cndmask_b32_e32 v25, v238, v25, vcc
	v_lshlrev_b32_e32 v25, 2, v25
	ds_bpermute_b32 v25, v25, v24
	s_waitcnt lgkmcnt(0)
	v_add_f32_e32 v24, v24, v25
	v_xor_b32_e32 v25, 32, v238
	v_cmp_lt_i32_e32 vcc, v25, v26
	s_nop 1
	v_cndmask_b32_e32 v25, v238, v25, vcc
	v_lshlrev_b32_e32 v25, 2, v25
	ds_bpermute_b32 v25, v25, v24
	s_and_b64 exec, exec, s[6:7]
	s_cbranch_execz .LBB0_1361
	s_waitcnt lgkmcnt(0)
	v_add_f32_e32 v24, v24, v25
	global_atomic_add_f32 v[8:9], v24, off
	s_branch .LBB0_1361
